# h2 ctx-token loop: the nine activation loads issued ahead of the bias and weight loads (long-latency loads first), waits recounted
# baseline (speedup 1.0000x reference)
; __device__ __forceinline__ float bf2f(bf16_t b) { return __uint_as_float(((unsigned)b) << 16); }
; __device__ __forceinline__ void h2_shortconv(const KQ p_in, int o, int M, unsigned char* smem) {
;     ...
;             const int t = idx >> 10, d = idx & 1023;
;             const int pos = (t - TL) & (CL - 1); const bool first = pos == 0, last = pos == CL - 1;
;             float zz[3];
; #pragma unroll
;             for (int k = 0; k < 3; ++k) {
;                 const int c = k * 1024 + d;
;                 float sacc = bs[c] + bf2f(ZH[(size_t)t * HYW + c]) * w[HYW + c];
;                 if (!first) sacc += bf2f(ZH[(size_t)(t - 1) * HYW + c]) * w[c];
;                 if (!last) sacc += bf2f(ZH[(size_t)(t + 1) * HYW + c]) * w[2 * HYW + c];
;                 zz[k] = sacc;
;             }
.LBB0_439:
	v_ashrrev_i32_e32 v6, 10, v0
	v_and_b32_e32 v1, 0x3ff, v0
	v_cmp_ne_u32_sdwa s[16:17], v6, v145 src0_sel:BYTE_0 src1_sel:DWORD
	v_cmp_ne_u32_sdwa s[18:19], v6, s31 src0_sel:BYTE_0 src1_sel:DWORD
	v_mul_u32_u24_e32 v2, 0x1800, v6
	v_lshlrev_b32_e32 v208, 2, v1
	v_lshl_add_u32 v2, v1, 1, v2
	v_add_u32_e32 v209, 0x1000, v208
	v_add_u32_e32 v210, 0x2000, v208
	v_add_u32_e32 v3, 0xffffe800, v2
	v_add_u32_e32 v4, 0x1800, v2
	v_cndmask_b32_e64 v3, v2, v3, s[16:17]
	v_cndmask_b32_e64 v4, v2, v4, s[18:19]
	v_add_u32_e32 v5, 0x1000, v2
	v_add_u32_e32 v7, 0x1000, v3
	v_add_u32_e32 v8, 0x1000, v4
	global_load_ushort v211, v2, s[8:9]
	global_load_ushort v212, v2, s[8:9] offset:2048
	global_load_ushort v213, v5, s[8:9]
	global_load_ushort v217, v3, s[8:9]
	global_load_ushort v218, v3, s[8:9] offset:2048
	global_load_ushort v219, v7, s[8:9]
	global_load_ushort v223, v4, s[8:9]
	global_load_ushort v224, v4, s[8:9] offset:2048
	global_load_ushort v225, v8, s[8:9]
	global_load_dword v12, v208, s[6:7]
	global_load_dword v10, v209, s[6:7]
	global_load_dword v1, v210, s[6:7]
	global_load_dword v214, v208, s[98:99]
	global_load_dword v215, v209, s[98:99]
	global_load_dword v216, v210, s[98:99]
	global_load_dword v220, v208, s[4:5]
	global_load_dword v221, v209, s[4:5]
	global_load_dword v222, v210, s[4:5]
	global_load_dword v226, v208, s[100:101]
	global_load_dword v227, v209, s[100:101]
	global_load_dword v228, v210, s[100:101]
	s_waitcnt vmcnt(6)
	v_lshlrev_b32_e32 v211, 16, v211
	v_lshlrev_b32_e32 v212, 16, v212
	v_lshlrev_b32_e32 v213, 16, v213
	v_fmac_f32_e32 v12, v214, v211
	v_fmac_f32_e32 v10, v215, v212
	v_fmac_f32_e32 v1, v216, v213
	s_waitcnt vmcnt(3)
	s_and_saveexec_b64 s[20:21], s[16:17]
	v_lshlrev_b32_e32 v217, 16, v217
	v_lshlrev_b32_e32 v218, 16, v218
	v_lshlrev_b32_e32 v219, 16, v219
	v_fmac_f32_e32 v12, v220, v217
	v_fmac_f32_e32 v10, v221, v218
	v_fmac_f32_e32 v1, v222, v219
	s_mov_b64 exec, s[20:21]
	s_waitcnt vmcnt(0)
	s_and_saveexec_b64 s[20:21], s[18:19]
	v_lshlrev_b32_e32 v223, 16, v223
	v_lshlrev_b32_e32 v224, 16, v224
	v_lshlrev_b32_e32 v225, 16, v225
	v_fmac_f32_e32 v12, v226, v223
	v_fmac_f32_e32 v10, v227, v224
	v_fmac_f32_e32 v1, v228, v225
	s_mov_b64 exec, s[20:21]
	s_branch .LBB0_438
